# v077 + final LN gamma/beta in registers (all in-loop drains removed)
# speedup vs baseline: 1.0090x; 1.0090x over previous
.LBB0_1691:
	s_mov_b64 s[4:5], s[0:1]
	s_load_dword s4, s[4:5], 0xe8
	s_add_i32 s21, s21, 3
	s_waitcnt lgkmcnt(0)
	s_cmp_gt_i32 s4, s21
	s_cbranch_scc1 .LBB0_1715
	s_mov_b64 s[4:5], s[0:1]
	s_load_dword s4, s[4:5], 0xec
	s_waitcnt lgkmcnt(0)
	s_cmp_ge_i32 s21, s4
	s_mov_b32 s21, 0x12000
	s_cbranch_scc1 .LBB0_1715
	s_xor_b64 s[6:7], s[70:71], -1
	s_mov_b64 s[4:5], -1
	s_and_b64 vcc, exec, s[6:7]
	s_cbranch_vccz .LBB0_1702
	s_mov_b64 s[4:5], s[0:1]
	s_mov_b64 s[6:7], s[0:1]
	s_mov_b64 s[8:9], s[0:1]
	s_mov_b64 s[12:13], s[0:1]
	v_mov_b32_e32 v0, v190
	s_nop 0
	v_readfirstlane_b32 s10, v0
	s_ashr_i32 s18, s10, 6
	s_mov_b32 s10, s2
	s_lshl_b32 s19, s10, 3
	s_add_i32 s10, s19, s18
	s_cmpk_gt_i32 s10, 0x3fff
	s_cbranch_scc1 .LBB0_1701
	s_load_dwordx2 s[8:9], s[8:9], 0xd0
	s_nop 0
	s_load_dwordx2 s[6:7], s[6:7], 0xc8
	s_nop 0
	s_load_dwordx2 s[4:5], s[4:5], 0xe0
	s_waitcnt vmcnt(0)
	v_and_b32_e32 v2, 63, v0
	v_lshlrev_b32_e32 v0, 4, v2
	s_waitcnt lgkmcnt(0)
	s_add_u32 s8, s8, 0x2000
	s_addc_u32 s9, s9, 0
	s_add_u32 s6, s6, 0x2000
	s_addc_u32 s7, s7, 0
	s_add_u32 s21, s4, 0x20100000
	s_addc_u32 s22, s5, 0
	s_ashr_i32 s11, s10, 31
	s_lshl_b64 s[4:5], s[10:11], 12
	s_add_u32 s4, s21, s4
	s_addc_u32 s5, s22, s5
	global_load_dwordx4 v[18:21], v0, s[4:5] offset:3072
	global_load_dwordx4 v[22:25], v0, s[4:5] offset:2048
	global_load_dwordx4 v[26:29], v0, s[4:5] offset:1024
	global_load_dwordx4 v[30:33], v0, s[4:5]
	s_load_dwordx2 s[14:15], s[12:13], 0xd8
	v_and_b32_e32 v6, 64, v197
	v_xor_b32_e32 v4, 16, v197
	v_add_u32_e32 v6, 64, v6
	v_xor_b32_e32 v8, 32, v197
	v_cmp_lt_i32_e32 vcc, v4, v6
	v_lshlrev_b32_e32 v2, 5, v2
	v_mov_b32_e32 v3, v1
	v_cndmask_b32_e32 v10, v197, v4, vcc
	v_cmp_lt_i32_e32 vcc, v8, v6
	v_mov_b32_e32 v5, v1
	v_mov_b32_e32 v7, v1
	v_mov_b32_e32 v9, v1
	v_cndmask_b32_e32 v11, v197, v8, vcc
	v_or_b32_e32 v4, 0x800, v2
	v_or_b32_e32 v6, 0x1000, v2
	v_or_b32_e32 v8, 0x1800, v2
	s_waitcnt lgkmcnt(0)
	s_cmp_lg_u64 s[14:15], 0
	v_lshl_add_u64 v[42:43], s[6:7], 0, v[2:3]
	v_lshl_add_u64 v[44:45], s[6:7], 0, v[4:5]
	v_lshl_add_u64 v[46:47], s[6:7], 0, v[6:7]
	v_lshl_add_u64 v[48:49], s[6:7], 0, v[8:9]
	s_cselect_b64 s[12:13], -1, 0
	s_add_i32 s6, s20, s18
	s_add_i32 s6, s6, s19
	s_ashr_i32 s7, s6, 31
	s_lshl_b64 s[6:7], s[6:7], 12
	s_add_u32 s6, s21, s6
	v_lshl_add_u64 v[34:35], s[8:9], 0, v[2:3]
	v_lshl_add_u64 v[36:37], s[8:9], 0, v[4:5]
	v_lshl_add_u64 v[38:39], s[8:9], 0, v[6:7]
	v_lshl_add_u64 v[40:41], s[8:9], 0, v[8:9]
	global_load_dwordx4 v[94:97], v[34:35], off
	global_load_dwordx4 v[98:101], v[34:35], off offset:16
	global_load_dwordx4 v[102:105], v[42:43], off
	global_load_dwordx4 v[106:109], v[42:43], off offset:16
	global_load_dwordx4 v[110:113], v[36:37], off
	global_load_dwordx4 v[130:133], v[36:37], off offset:16
	global_load_dwordx4 v[134:137], v[44:45], off
	global_load_dwordx4 v[138:141], v[44:45], off offset:16
	global_load_dwordx4 v[142:145], v[38:39], off
	global_load_dwordx4 v[158:161], v[38:39], off offset:16
	global_load_dwordx4 v[162:165], v[46:47], off
	global_load_dwordx4 v[166:169], v[46:47], off offset:16
	global_load_dwordx4 v[170:173], v[40:41], off
	global_load_dwordx4 v[176:179], v[40:41], off offset:16
	global_load_dwordx4 v[180:183], v[48:49], off
	global_load_dwordx4 v[184:187], v[48:49], off offset:16
	s_addc_u32 s7, s22, s7
	s_lshl_b64 s[8:9], s[10:11], 13
	v_lshl_add_u64 v[50:51], s[6:7], 0, v[0:1]
	s_add_u32 s6, s14, s8
	s_addc_u32 s7, s15, s9
	s_mov_b64 s[4:5], 0x1000
	v_lshl_add_u64 v[2:3], s[6:7], 0, v[2:3]
	v_lshlrev_b32_e32 v70, 2, v10
	v_lshlrev_b32_e32 v71, 2, v11
	v_lshl_add_u64 v[52:53], v[2:3], 0, s[4:5]
	s_mov_b32 s21, 0x12000
	s_waitcnt vmcnt(0)
	v_mov_b64_e32 v[2:3], v[18:19]
	s_waitcnt vmcnt(2)
	v_mov_b64_e32 v[6:7], v[22:23]
	s_waitcnt vmcnt(1)
	v_mov_b64_e32 v[10:11], v[26:27]
	s_waitcnt vmcnt(0)
	v_mov_b64_e32 v[14:15], v[30:31]
	v_mov_b64_e32 v[4:5], v[20:21]
	v_mov_b64_e32 v[8:9], v[24:25]
	v_mov_b64_e32 v[12:13], v[28:29]
	v_mov_b64_e32 v[16:17], v[32:33]
	s_branch .LBB0_1697

.LBB0_1699:
	v_lshlrev_b32_e32 v64, 16, v30
	v_and_b32_e32 v65, 0xffff0000, v30
	v_lshlrev_b32_e32 v62, 16, v31
	v_and_b32_e32 v63, 0xffff0000, v31
	v_lshlrev_b32_e32 v66, 16, v32
	v_and_b32_e32 v67, 0xffff0000, v32
	v_lshlrev_b32_e32 v68, 16, v33
	v_and_b32_e32 v69, 0xffff0000, v33
	v_add_f32_e32 v0, v64, v65
	s_waitcnt lgkmcnt(0)
	v_add_f32_e32 v72, v62, v63
	v_add_f32_e32 v0, v0, v72
	v_add_f32_e32 v72, v66, v67
	v_add_f32_e32 v73, v68, v69
	v_lshlrev_b32_e32 v54, 16, v26
	v_and_b32_e32 v55, 0xffff0000, v26
	v_lshlrev_b32_e32 v56, 16, v27
	v_and_b32_e32 v57, 0xffff0000, v27
	v_add_f32_e32 v0, 0, v0
	v_add_f32_e32 v72, v72, v73
	v_add_f32_e32 v0, v72, v0
	v_add_f32_e32 v72, v54, v55
	v_add_f32_e32 v73, v56, v57
	v_lshlrev_b32_e32 v58, 16, v28
	v_and_b32_e32 v59, 0xffff0000, v28
	v_lshlrev_b32_e32 v60, 16, v29
	v_and_b32_e32 v61, 0xffff0000, v29
	v_add_f32_e32 v72, v72, v73
	v_add_f32_e32 v0, v72, v0
	v_add_f32_e32 v72, v58, v59
	v_add_f32_e32 v73, v60, v61
	v_lshlrev_b32_e32 v26, 16, v22
	v_and_b32_e32 v27, 0xffff0000, v22
	v_lshlrev_b32_e32 v28, 16, v23
	v_and_b32_e32 v29, 0xffff0000, v23
	v_add_f32_e32 v72, v72, v73
	v_add_f32_e32 v0, v72, v0
	v_add_f32_e32 v72, v26, v27
	v_add_f32_e32 v73, v28, v29
	v_lshlrev_b32_e32 v30, 16, v24
	v_and_b32_e32 v31, 0xffff0000, v24
	v_lshlrev_b32_e32 v32, 16, v25
	v_and_b32_e32 v33, 0xffff0000, v25
	v_add_f32_e32 v72, v72, v73
	v_add_f32_e32 v0, v72, v0
	v_add_f32_e32 v72, v30, v31
	v_add_f32_e32 v73, v32, v33
	v_lshlrev_b32_e32 v22, 16, v18
	v_and_b32_e32 v23, 0xffff0000, v18
	v_lshlrev_b32_e32 v18, 16, v19
	v_and_b32_e32 v19, 0xffff0000, v19
	v_add_f32_e32 v72, v72, v73
	v_add_f32_e32 v0, v72, v0
	v_add_f32_e32 v72, v22, v23
	v_add_f32_e32 v73, v18, v19
	v_lshlrev_b32_e32 v24, 16, v20
	v_and_b32_e32 v25, 0xffff0000, v20
	v_lshlrev_b32_e32 v20, 16, v21
	v_and_b32_e32 v21, 0xffff0000, v21
	v_add_f32_e32 v72, v72, v73
	v_add_f32_e32 v0, v72, v0
	v_add_f32_e32 v72, v24, v25
	v_add_f32_e32 v73, v20, v21
	v_add_f32_e32 v72, v72, v73
	v_add_f32_e32 v0, v72, v0
	s_andn2_b64 vcc, exec, s[12:13]
	s_nop 0
	v_add_f32_dpp v0, v0, v0 quad_perm:[1,0,3,2] row_mask:0xf bank_mask:0xf bound_ctrl:1
	s_nop 1
	v_add_f32_dpp v0, v0, v0 quad_perm:[2,3,0,1] row_mask:0xf bank_mask:0xf bound_ctrl:1
	s_nop 1
	v_add_f32_dpp v0, v0, v0 row_half_mirror row_mask:0xf bank_mask:0xf bound_ctrl:1
	s_nop 1
	v_add_f32_dpp v0, v0, v0 row_ror:8 row_mask:0xf bank_mask:0xf bound_ctrl:1
	ds_bpermute_b32 v72, v70, v0
	s_waitcnt lgkmcnt(0)
	v_add_f32_e32 v0, v0, v72
	ds_bpermute_b32 v72, v71, v0
	s_waitcnt lgkmcnt(0)
	v_add_f32_e32 v0, v0, v72
	v_fmac_f32_e32 v63, 0xba000000, v0
	v_fmac_f32_e32 v65, 0xba000000, v0
	v_fmac_f32_e32 v62, 0xba000000, v0
	v_fmac_f32_e32 v64, 0xba000000, v0
	v_mul_f32_e32 v72, v65, v65
	v_mul_f32_e32 v73, v63, v63
	v_fmac_f32_e32 v72, v64, v64
	v_fmac_f32_e32 v73, v62, v62
	v_fmac_f32_e32 v69, 0xba000000, v0
	v_fmac_f32_e32 v67, 0xba000000, v0
	v_add_f32_e32 v72, v72, v73
	v_fmac_f32_e32 v68, 0xba000000, v0
	v_fmac_f32_e32 v66, 0xba000000, v0
	v_mul_f32_e32 v73, v67, v67
	v_mul_f32_e32 v74, v69, v69
	v_fmac_f32_e32 v73, v66, v66
	v_fmac_f32_e32 v74, v68, v68
	v_add_f32_e32 v73, v73, v74
	v_fmac_f32_e32 v57, 0xba000000, v0
	v_fmac_f32_e32 v55, 0xba000000, v0
	v_add_f32_e32 v72, v72, v73
	v_fmac_f32_e32 v56, 0xba000000, v0
	v_fmac_f32_e32 v54, 0xba000000, v0
	v_mul_f32_e32 v73, v55, v55
	v_mul_f32_e32 v74, v57, v57
	v_fmac_f32_e32 v73, v54, v54
	v_fmac_f32_e32 v74, v56, v56
	v_add_f32_e32 v73, v73, v74
	v_fmac_f32_e32 v61, 0xba000000, v0
	v_fmac_f32_e32 v59, 0xba000000, v0
	v_add_f32_e32 v72, v73, v72
	v_fmac_f32_e32 v60, 0xba000000, v0
	v_fmac_f32_e32 v58, 0xba000000, v0
	v_mul_f32_e32 v73, v59, v59
	v_mul_f32_e32 v74, v61, v61
	v_fmac_f32_e32 v73, v58, v58
	v_fmac_f32_e32 v74, v60, v60
	v_add_f32_e32 v73, v73, v74
	v_fmac_f32_e32 v29, 0xba000000, v0
	v_fmac_f32_e32 v27, 0xba000000, v0
	v_add_f32_e32 v72, v73, v72
	v_fmac_f32_e32 v28, 0xba000000, v0
	v_fmac_f32_e32 v26, 0xba000000, v0
	v_mul_f32_e32 v73, v27, v27
	v_mul_f32_e32 v74, v29, v29
	v_fmac_f32_e32 v73, v26, v26
	v_fmac_f32_e32 v74, v28, v28
	v_add_f32_e32 v73, v73, v74
	v_fmac_f32_e32 v33, 0xba000000, v0
	v_fmac_f32_e32 v31, 0xba000000, v0
	v_add_f32_e32 v72, v73, v72
	v_fmac_f32_e32 v32, 0xba000000, v0
	v_fmac_f32_e32 v30, 0xba000000, v0
	v_mul_f32_e32 v73, v31, v31
	v_mul_f32_e32 v74, v33, v33
	v_fmac_f32_e32 v73, v30, v30
	v_fmac_f32_e32 v74, v32, v32
	v_add_f32_e32 v73, v73, v74
	v_fmac_f32_e32 v19, 0xba000000, v0
	v_fmac_f32_e32 v23, 0xba000000, v0
	v_add_f32_e32 v72, v73, v72
	v_fmac_f32_e32 v18, 0xba000000, v0
	v_fmac_f32_e32 v22, 0xba000000, v0
	v_mul_f32_e32 v73, v23, v23
	v_mul_f32_e32 v74, v19, v19
	v_fmac_f32_e32 v73, v22, v22
	v_fmac_f32_e32 v74, v18, v18
	v_add_f32_e32 v73, v73, v74
	v_fmac_f32_e32 v21, 0xba000000, v0
	v_fmac_f32_e32 v25, 0xba000000, v0
	v_add_f32_e32 v72, v73, v72
	v_fmac_f32_e32 v20, 0xba000000, v0
	v_fmac_f32_e32 v24, 0xba000000, v0
	v_mul_f32_e32 v0, v25, v25
	v_mul_f32_e32 v73, v21, v21
	v_fmac_f32_e32 v0, v24, v24
	v_fmac_f32_e32 v73, v20, v20
	v_add_f32_e32 v0, v0, v73
	v_add_f32_e32 v0, v0, v72
	s_nop 1
	v_add_f32_dpp v0, v0, v0 quad_perm:[1,0,3,2] row_mask:0xf bank_mask:0xf bound_ctrl:1
	s_nop 1
	v_add_f32_dpp v0, v0, v0 quad_perm:[2,3,0,1] row_mask:0xf bank_mask:0xf bound_ctrl:1
	s_nop 1
	v_add_f32_dpp v0, v0, v0 row_half_mirror row_mask:0xf bank_mask:0xf bound_ctrl:1
	s_nop 1
	v_add_f32_dpp v0, v0, v0 row_ror:8 row_mask:0xf bank_mask:0xf bound_ctrl:1
	ds_bpermute_b32 v72, v70, v0
	s_waitcnt lgkmcnt(0)
	v_add_f32_e32 v0, v0, v72
	ds_bpermute_b32 v72, v71, v0
	s_cbranch_vccnz .LBB0_1696
	s_waitcnt lgkmcnt(0)
	v_add_f32_e32 v0, v0, v72
	v_fmamk_f32 v0, v0, 0x3a000000, v198
	v_mul_f32_e32 v72, 0x4f800000, v0
	v_cmp_gt_f32_e32 vcc, s84, v0
	s_nop 1
	v_cndmask_b32_e32 v0, v0, v72, vcc
	v_sqrt_f32_e32 v72, v0
	s_nop 0
	v_add_u32_e32 v73, -1, v72
	v_add_u32_e32 v90, 1, v72
	v_fma_f32 v91, -v73, v72, v0
	v_fma_f32 v92, -v90, v72, v0
	v_cmp_ge_f32_e64 s[8:9], 0, v91
	s_nop 1
	v_cndmask_b32_e64 v72, v72, v73, s[8:9]
	v_cmp_lt_f32_e64 s[8:9], 0, v92
	s_nop 1
	v_cndmask_b32_e64 v72, v72, v90, s[8:9]
	v_mul_f32_e32 v73, 0x37800000, v72
	v_cndmask_b32_e32 v72, v72, v73, vcc
	v_cmp_class_f32_e32 vcc, v0, v199
	s_nop 1
	v_cndmask_b32_e32 v0, v72, v0, vcc
	v_div_scale_f32 v72, s[4:5], v0, v0, 1.0
	v_rcp_f32_e32 v73, v72
	v_div_scale_f32 v90, vcc, 1.0, v0, 1.0
	v_fma_f32 v91, -v72, v73, 1.0
	v_fmac_f32_e32 v73, v91, v73
	v_mul_f32_e32 v91, v90, v73
	v_fma_f32 v92, -v72, v91, v90
	v_fmac_f32_e32 v91, v92, v73
	v_fma_f32 v72, -v72, v91, v90
	v_div_fmas_f32 v72, v72, v73, v91
	v_div_fixup_f32 v0, v72, v0, 1.0
	v_pk_mul_f32 v[66:67], v[66:67], v[0:1] op_sel_hi:[1,0]
	v_pk_mul_f32 v[68:69], v[68:69], v[0:1] op_sel_hi:[1,0]
	v_pk_mul_f32 v[72:73], v[64:65], v[0:1] op_sel_hi:[1,0]
	v_pk_mul_f32 v[90:91], v[62:63], v[0:1] op_sel_hi:[1,0]
	v_pk_mul_f32 v[60:61], v[60:61], v[0:1] op_sel_hi:[1,0]
	v_pk_mul_f32 v[58:59], v[58:59], v[0:1] op_sel_hi:[1,0]
	v_pk_mul_f32 v[32:33], v[32:33], v[0:1] op_sel_hi:[1,0]
	v_pk_mul_f32 v[30:31], v[30:31], v[0:1] op_sel_hi:[1,0]
	v_pk_mul_f32 v[24:25], v[24:25], v[0:1] op_sel_hi:[1,0]
	v_pk_mul_f32 v[22:23], v[22:23], v[0:1] op_sel_hi:[1,0]
	v_pk_mul_f32 v[20:21], v[20:21], v[0:1] op_sel_hi:[1,0]
	v_pk_fma_f32 v[64:65], v[68:69], v[108:109], v[100:101]
	v_pk_fma_f32 v[62:63], v[66:67], v[106:107], v[98:99]
	v_pk_fma_f32 v[68:69], v[90:91], v[104:105], v[96:97]
	v_pk_fma_f32 v[66:67], v[72:73], v[102:103], v[94:95]
	global_store_dwordx4 v[52:53], v[66:69], off offset:-4096
	s_nop 1
	global_store_dwordx4 v[52:53], v[62:65], off offset:-4080
	s_nop 1
	s_nop 0
	v_pk_mul_f32 v[80:81], v[56:57], v[0:1] op_sel_hi:[1,0]
	v_pk_mul_f32 v[82:83], v[54:55], v[0:1] op_sel_hi:[1,0]
	v_pk_fma_f32 v[54:55], v[58:59], v[138:139], v[130:131]
	v_pk_fma_f32 v[56:57], v[60:61], v[140:141], v[132:133]
	v_pk_fma_f32 v[58:59], v[82:83], v[134:135], v[110:111]
	v_pk_fma_f32 v[60:61], v[80:81], v[136:137], v[112:113]
	global_store_dwordx4 v[52:53], v[58:61], off offset:-2048
	s_nop 1
	global_store_dwordx4 v[52:53], v[54:57], off offset:-2032
	s_nop 1
	s_nop 0
	v_pk_mul_f32 v[72:73], v[28:29], v[0:1] op_sel_hi:[1,0]
	v_pk_mul_f32 v[74:75], v[26:27], v[0:1] op_sel_hi:[1,0]
	v_pk_fma_f32 v[26:27], v[30:31], v[166:167], v[158:159]
	v_pk_fma_f32 v[28:29], v[32:33], v[168:169], v[160:161]
	v_pk_fma_f32 v[30:31], v[74:75], v[162:163], v[142:143]
	v_pk_fma_f32 v[32:33], v[72:73], v[164:165], v[144:145]
	global_store_dwordx4 v[52:53], v[30:33], off
	s_nop 1
	global_store_dwordx4 v[52:53], v[26:29], off offset:16
	s_nop 1
	s_nop 0
	v_pk_mul_f32 v[62:63], v[18:19], v[0:1] op_sel_hi:[1,0]
	v_pk_fma_f32 v[18:19], v[24:25], v[184:185], v[176:177]
	v_pk_fma_f32 v[20:21], v[20:21], v[186:187], v[178:179]
	v_pk_fma_f32 v[22:23], v[22:23], v[180:181], v[170:171]
	v_pk_fma_f32 v[24:25], v[62:63], v[182:183], v[172:173]
	global_store_dwordx4 v[52:53], v[22:25], off offset:2048
	s_nop 1
	global_store_dwordx4 v[52:53], v[18:21], off offset:2064
	s_nop 1
	s_waitcnt vmcnt(8)
	s_nop 1
	s_branch .Lln24_rot
